# merge-GEMM (GEMM2) epilogues rewritten by hand: gate loads hoisted/pipelined (z=1: all 16 up front; z=0: 5 row-groups deep) instead of 24 serialized round trips
# baseline (speedup 1.0000x reference)
.LBB0_775:
	v_lshl_add_u32 v158, s16, 8, v1
	v_lshl_or_b32 v4, s17, 8, v165
	v_ashrrev_i32_e32 v159, 31, v158
	v_ashrrev_i32_e32 v5, 31, v4
	v_lshlrev_b64 v[134:135], 12, v[158:159]
	s_cmp_lg_u32 s38, 0
	v_lshl_add_u64 v[136:137], s[74:75], 0, v[134:135]
	v_lshlrev_b64 v[134:135], 1, v[4:5]
	s_cselect_b64 s[16:17], -1, 0
	s_cmp_eq_u32 s38, 0
	v_lshl_add_u64 v[4:5], v[136:137], 0, v[134:135]
	v_or_b32_e32 v140, 16, v158
	v_or_b32_e32 v138, 32, v158
	v_or_b32_e32 v136, 48, v158
	s_cbranch_scc1 .Lepi2_z0
	s_nop 7
	s_nop 7
	v_lshlrev_b64 v[248:249], 11, v[158:159]
	v_lshl_add_u64 v[248:249], s[46:47], 0, v[248:249]
	v_lshl_add_u64 v[248:249], v[248:249], 0, v[134:135]
	v_mov_b64_e32 v[172:173], v[4:5]
	global_load_dwordx4 v[168:171], v[172:173], off offset:2048
	global_load_dwordx4 v[172:175], v[172:173], off offset:2304
	v_add_co_u32_e32 v180, vcc, 0x10000, v4
	s_nop 1
	v_addc_co_u32_e32 v181, vcc, 0, v5, vcc
	global_load_dwordx4 v[176:179], v[180:181], off offset:2048
	global_load_dwordx4 v[180:183], v[180:181], off offset:2304
	v_add_co_u32_e32 v188, vcc, 0x20000, v4
	s_nop 1
	v_addc_co_u32_e32 v189, vcc, 0, v5, vcc
	global_load_dwordx4 v[184:187], v[188:189], off offset:2048
	global_load_dwordx4 v[188:191], v[188:189], off offset:2304
	v_add_co_u32_e32 v196, vcc, 0x30000, v4
	s_nop 1
	v_addc_co_u32_e32 v197, vcc, 0, v5, vcc
	global_load_dwordx4 v[192:195], v[196:197], off offset:2048
	global_load_dwordx4 v[196:199], v[196:197], off offset:2304
	v_add_co_u32_e32 v204, vcc, 0x80000, v4
	s_nop 1
	v_addc_co_u32_e32 v205, vcc, 0, v5, vcc
	global_load_dwordx4 v[200:203], v[204:205], off offset:2048
	global_load_dwordx4 v[204:207], v[204:205], off offset:2304
	v_add_co_u32_e32 v212, vcc, 0x90000, v4
	s_nop 1
	v_addc_co_u32_e32 v213, vcc, 0, v5, vcc
	global_load_dwordx4 v[208:211], v[212:213], off offset:2048
	global_load_dwordx4 v[212:215], v[212:213], off offset:2304
	v_add_co_u32_e32 v228, vcc, 0xa0000, v4
	s_nop 1
	v_addc_co_u32_e32 v229, vcc, 0, v5, vcc
	global_load_dwordx4 v[220:223], v[228:229], off offset:2048
	global_load_dwordx4 v[228:231], v[228:229], off offset:2304
	v_add_co_u32_e32 v236, vcc, 0xb0000, v4
	s_nop 1
	v_addc_co_u32_e32 v237, vcc, 0, v5, vcc
	global_load_dwordx4 v[232:235], v[236:237], off offset:2048
	global_load_dwordx4 v[236:239], v[236:237], off offset:2304
	s_waitcnt vmcnt(15)
	v_lshlrev_b32_e32 v138, 16, v168
	v_and_b32_e32 v139, 0xffff0000, v168
	v_rcp_f32_e32 v138, v138
	v_rcp_f32_e32 v139, v139
	s_nop 0
	v_mul_f32_e32 v138, v130, v138
	v_mul_f32_e32 v139, v131, v139
	v_cvt_pk_bf16_f32 v168, v138, v139
	v_lshlrev_b32_e32 v158, 16, v169
	v_and_b32_e32 v159, 0xffff0000, v169
	v_rcp_f32_e32 v158, v158
	v_rcp_f32_e32 v159, v159
	s_nop 0
	v_mul_f32_e32 v158, v132, v158
	v_mul_f32_e32 v159, v133, v159
	v_cvt_pk_bf16_f32 v169, v158, v159
	v_lshlrev_b32_e32 v138, 16, v170
	v_and_b32_e32 v139, 0xffff0000, v170
	v_rcp_f32_e32 v138, v138
	v_rcp_f32_e32 v139, v139
	s_nop 0
	v_mul_f32_e32 v138, v126, v138
	v_mul_f32_e32 v139, v127, v139
	v_cvt_pk_bf16_f32 v170, v138, v139
	v_lshlrev_b32_e32 v158, 16, v171
	v_and_b32_e32 v159, 0xffff0000, v171
	v_rcp_f32_e32 v158, v158
	v_rcp_f32_e32 v159, v159
	s_nop 0
	v_mul_f32_e32 v158, v128, v158
	v_mul_f32_e32 v159, v129, v159
	v_cvt_pk_bf16_f32 v171, v158, v159
	global_store_dwordx4 v[248:249], v[168:171], off
	s_waitcnt vmcnt(15)
	v_lshlrev_b32_e32 v138, 16, v172
	v_and_b32_e32 v139, 0xffff0000, v172
	v_rcp_f32_e32 v138, v138
	v_rcp_f32_e32 v139, v139
	s_nop 0
	v_mul_f32_e32 v138, v98, v138
	v_mul_f32_e32 v139, v99, v139
	v_cvt_pk_bf16_f32 v172, v138, v139
	v_lshlrev_b32_e32 v158, 16, v173
	v_and_b32_e32 v159, 0xffff0000, v173
	v_rcp_f32_e32 v158, v158
	v_rcp_f32_e32 v159, v159
	s_nop 0
	v_mul_f32_e32 v158, v100, v158
	v_mul_f32_e32 v159, v101, v159
	v_cvt_pk_bf16_f32 v173, v158, v159
	v_lshlrev_b32_e32 v138, 16, v174
	v_and_b32_e32 v139, 0xffff0000, v174
	v_rcp_f32_e32 v138, v138
	v_rcp_f32_e32 v139, v139
	s_nop 0
	v_mul_f32_e32 v138, v94, v138
	v_mul_f32_e32 v139, v95, v139
	v_cvt_pk_bf16_f32 v174, v138, v139
	v_lshlrev_b32_e32 v158, 16, v175
	v_and_b32_e32 v159, 0xffff0000, v175
	v_rcp_f32_e32 v158, v158
	v_rcp_f32_e32 v159, v159
	s_nop 0
	v_mul_f32_e32 v158, v96, v158
	v_mul_f32_e32 v159, v97, v159
	v_cvt_pk_bf16_f32 v175, v158, v159
	global_store_dwordx4 v[248:249], v[172:175], off offset:256
	v_add_co_u32_e32 v248, vcc, 0x8000, v248
	s_nop 1
	v_addc_co_u32_e32 v249, vcc, 0, v249, vcc
	s_waitcnt vmcnt(15)
	v_lshlrev_b32_e32 v138, 16, v176
	v_and_b32_e32 v139, 0xffff0000, v176
	v_rcp_f32_e32 v138, v138
	v_rcp_f32_e32 v139, v139
	s_nop 0
	v_mul_f32_e32 v138, v122, v138
	v_mul_f32_e32 v139, v123, v139
	v_cvt_pk_bf16_f32 v176, v138, v139
	v_lshlrev_b32_e32 v158, 16, v177
	v_and_b32_e32 v159, 0xffff0000, v177
	v_rcp_f32_e32 v158, v158
	v_rcp_f32_e32 v159, v159
	s_nop 0
	v_mul_f32_e32 v158, v124, v158
	v_mul_f32_e32 v159, v125, v159
	v_cvt_pk_bf16_f32 v177, v158, v159
	v_lshlrev_b32_e32 v138, 16, v178
	v_and_b32_e32 v139, 0xffff0000, v178
	v_rcp_f32_e32 v138, v138
	v_rcp_f32_e32 v139, v139
	s_nop 0
	v_mul_f32_e32 v138, v118, v138
	v_mul_f32_e32 v139, v119, v139
	v_cvt_pk_bf16_f32 v178, v138, v139
	v_lshlrev_b32_e32 v158, 16, v179
	v_and_b32_e32 v159, 0xffff0000, v179
	v_rcp_f32_e32 v158, v158
	v_rcp_f32_e32 v159, v159
	s_nop 0
	v_mul_f32_e32 v158, v120, v158
	v_mul_f32_e32 v159, v121, v159
	v_cvt_pk_bf16_f32 v179, v158, v159
	global_store_dwordx4 v[248:249], v[176:179], off
	s_waitcnt vmcnt(15)
	v_lshlrev_b32_e32 v138, 16, v180
	v_and_b32_e32 v139, 0xffff0000, v180
	v_rcp_f32_e32 v138, v138
	v_rcp_f32_e32 v139, v139
	s_nop 0
	v_mul_f32_e32 v138, v90, v138
	v_mul_f32_e32 v139, v91, v139
	v_cvt_pk_bf16_f32 v180, v138, v139
	v_lshlrev_b32_e32 v158, 16, v181
	v_and_b32_e32 v159, 0xffff0000, v181
	v_rcp_f32_e32 v158, v158
	v_rcp_f32_e32 v159, v159
	s_nop 0
	v_mul_f32_e32 v158, v92, v158
	v_mul_f32_e32 v159, v93, v159
	v_cvt_pk_bf16_f32 v181, v158, v159
	v_lshlrev_b32_e32 v138, 16, v182
	v_and_b32_e32 v139, 0xffff0000, v182
	v_rcp_f32_e32 v138, v138
	v_rcp_f32_e32 v139, v139
	s_nop 0
	v_mul_f32_e32 v138, v86, v138
	v_mul_f32_e32 v139, v87, v139
	v_cvt_pk_bf16_f32 v182, v138, v139
	v_lshlrev_b32_e32 v158, 16, v183
	v_and_b32_e32 v159, 0xffff0000, v183
	v_rcp_f32_e32 v158, v158
	v_rcp_f32_e32 v159, v159
	s_nop 0
	v_mul_f32_e32 v158, v88, v158
	v_mul_f32_e32 v159, v89, v159
	v_cvt_pk_bf16_f32 v183, v158, v159
	global_store_dwordx4 v[248:249], v[180:183], off offset:256
	v_add_co_u32_e32 v248, vcc, 0x8000, v248
	s_nop 1
	v_addc_co_u32_e32 v249, vcc, 0, v249, vcc
	s_waitcnt vmcnt(15)
	v_lshlrev_b32_e32 v138, 16, v184
	v_and_b32_e32 v139, 0xffff0000, v184
	v_rcp_f32_e32 v138, v138
	v_rcp_f32_e32 v139, v139
	s_nop 0
	v_mul_f32_e32 v138, v114, v138
	v_mul_f32_e32 v139, v115, v139
	v_cvt_pk_bf16_f32 v184, v138, v139
	v_lshlrev_b32_e32 v158, 16, v185
	v_and_b32_e32 v159, 0xffff0000, v185
	v_rcp_f32_e32 v158, v158
	v_rcp_f32_e32 v159, v159
	s_nop 0
	v_mul_f32_e32 v158, v116, v158
	v_mul_f32_e32 v159, v117, v159
	v_cvt_pk_bf16_f32 v185, v158, v159
	v_lshlrev_b32_e32 v138, 16, v186
	v_and_b32_e32 v139, 0xffff0000, v186
	v_rcp_f32_e32 v138, v138
	v_rcp_f32_e32 v139, v139
	s_nop 0
	v_mul_f32_e32 v138, v110, v138
	v_mul_f32_e32 v139, v111, v139
	v_cvt_pk_bf16_f32 v186, v138, v139
	v_lshlrev_b32_e32 v158, 16, v187
	v_and_b32_e32 v159, 0xffff0000, v187
	v_rcp_f32_e32 v158, v158
	v_rcp_f32_e32 v159, v159
	s_nop 0
	v_mul_f32_e32 v158, v112, v158
	v_mul_f32_e32 v159, v113, v159
	v_cvt_pk_bf16_f32 v187, v158, v159
	global_store_dwordx4 v[248:249], v[184:187], off
	s_waitcnt vmcnt(15)
	v_lshlrev_b32_e32 v138, 16, v188
	v_and_b32_e32 v139, 0xffff0000, v188
	v_rcp_f32_e32 v138, v138
	v_rcp_f32_e32 v139, v139
	s_nop 0
	v_mul_f32_e32 v138, v82, v138
	v_mul_f32_e32 v139, v83, v139
	v_cvt_pk_bf16_f32 v188, v138, v139
	v_lshlrev_b32_e32 v158, 16, v189
	v_and_b32_e32 v159, 0xffff0000, v189
	v_rcp_f32_e32 v158, v158
	v_rcp_f32_e32 v159, v159
	s_nop 0
	v_mul_f32_e32 v158, v84, v158
	v_mul_f32_e32 v159, v85, v159
	v_cvt_pk_bf16_f32 v189, v158, v159
	v_lshlrev_b32_e32 v138, 16, v190
	v_and_b32_e32 v139, 0xffff0000, v190
	v_rcp_f32_e32 v138, v138
	v_rcp_f32_e32 v139, v139
	s_nop 0
	v_mul_f32_e32 v138, v78, v138
	v_mul_f32_e32 v139, v79, v139
	v_cvt_pk_bf16_f32 v190, v138, v139
	v_lshlrev_b32_e32 v158, 16, v191
	v_and_b32_e32 v159, 0xffff0000, v191
	v_rcp_f32_e32 v158, v158
	v_rcp_f32_e32 v159, v159
	s_nop 0
	v_mul_f32_e32 v158, v80, v158
	v_mul_f32_e32 v159, v81, v159
	v_cvt_pk_bf16_f32 v191, v158, v159
	global_store_dwordx4 v[248:249], v[188:191], off offset:256
	v_add_co_u32_e32 v248, vcc, 0x8000, v248
	s_nop 1
	v_addc_co_u32_e32 v249, vcc, 0, v249, vcc
	s_waitcnt vmcnt(15)
	v_lshlrev_b32_e32 v138, 16, v192
	v_and_b32_e32 v139, 0xffff0000, v192
	v_rcp_f32_e32 v138, v138
	v_rcp_f32_e32 v139, v139
	s_nop 0
	v_mul_f32_e32 v138, v106, v138
	v_mul_f32_e32 v139, v107, v139
	v_cvt_pk_bf16_f32 v192, v138, v139
	v_lshlrev_b32_e32 v158, 16, v193
	v_and_b32_e32 v159, 0xffff0000, v193
	v_rcp_f32_e32 v158, v158
	v_rcp_f32_e32 v159, v159
	s_nop 0
	v_mul_f32_e32 v158, v108, v158
	v_mul_f32_e32 v159, v109, v159
	v_cvt_pk_bf16_f32 v193, v158, v159
	v_lshlrev_b32_e32 v138, 16, v194
	v_and_b32_e32 v139, 0xffff0000, v194
	v_rcp_f32_e32 v138, v138
	v_rcp_f32_e32 v139, v139
	s_nop 0
	v_mul_f32_e32 v138, v102, v138
	v_mul_f32_e32 v139, v103, v139
	v_cvt_pk_bf16_f32 v194, v138, v139
	v_lshlrev_b32_e32 v158, 16, v195
	v_and_b32_e32 v159, 0xffff0000, v195
	v_rcp_f32_e32 v158, v158
	v_rcp_f32_e32 v159, v159
	s_nop 0
	v_mul_f32_e32 v158, v104, v158
	v_mul_f32_e32 v159, v105, v159
	v_cvt_pk_bf16_f32 v195, v158, v159
	global_store_dwordx4 v[248:249], v[192:195], off
	s_waitcnt vmcnt(15)
	v_lshlrev_b32_e32 v138, 16, v196
	v_and_b32_e32 v139, 0xffff0000, v196
	v_rcp_f32_e32 v138, v138
	v_rcp_f32_e32 v139, v139
	s_nop 0
	v_mul_f32_e32 v138, v74, v138
	v_mul_f32_e32 v139, v75, v139
	v_cvt_pk_bf16_f32 v196, v138, v139
	v_lshlrev_b32_e32 v158, 16, v197
	v_and_b32_e32 v159, 0xffff0000, v197
	v_rcp_f32_e32 v158, v158
	v_rcp_f32_e32 v159, v159
	s_nop 0
	v_mul_f32_e32 v158, v76, v158
	v_mul_f32_e32 v159, v77, v159
	v_cvt_pk_bf16_f32 v197, v158, v159
	v_lshlrev_b32_e32 v138, 16, v198
	v_and_b32_e32 v139, 0xffff0000, v198
	v_rcp_f32_e32 v138, v138
	v_rcp_f32_e32 v139, v139
	s_nop 0
	v_mul_f32_e32 v138, v70, v138
	v_mul_f32_e32 v139, v71, v139
	v_cvt_pk_bf16_f32 v198, v138, v139
	v_lshlrev_b32_e32 v158, 16, v199
	v_and_b32_e32 v159, 0xffff0000, v199
	v_rcp_f32_e32 v158, v158
	v_rcp_f32_e32 v159, v159
	s_nop 0
	v_mul_f32_e32 v158, v72, v158
	v_mul_f32_e32 v159, v73, v159
	v_cvt_pk_bf16_f32 v199, v158, v159
	global_store_dwordx4 v[248:249], v[196:199], off offset:256
	v_add_co_u32_e32 v248, vcc, 0x28000, v248
	s_nop 1
	v_addc_co_u32_e32 v249, vcc, 0, v249, vcc
	s_waitcnt vmcnt(15)
	v_lshlrev_b32_e32 v138, 16, v200
	v_and_b32_e32 v139, 0xffff0000, v200
	v_rcp_f32_e32 v138, v138
	v_rcp_f32_e32 v139, v139
	s_nop 0
	v_mul_f32_e32 v138, v66, v138
	v_mul_f32_e32 v139, v67, v139
	v_cvt_pk_bf16_f32 v200, v138, v139
	v_lshlrev_b32_e32 v158, 16, v201
	v_and_b32_e32 v159, 0xffff0000, v201
	v_rcp_f32_e32 v158, v158
	v_rcp_f32_e32 v159, v159
	s_nop 0
	v_mul_f32_e32 v158, v68, v158
	v_mul_f32_e32 v159, v69, v159
	v_cvt_pk_bf16_f32 v201, v158, v159
	v_lshlrev_b32_e32 v138, 16, v202
	v_and_b32_e32 v139, 0xffff0000, v202
	v_rcp_f32_e32 v138, v138
	v_rcp_f32_e32 v139, v139
	s_nop 0
	v_mul_f32_e32 v138, v62, v138
	v_mul_f32_e32 v139, v63, v139
	v_cvt_pk_bf16_f32 v202, v138, v139
	v_lshlrev_b32_e32 v158, 16, v203
	v_and_b32_e32 v159, 0xffff0000, v203
	v_rcp_f32_e32 v158, v158
	v_rcp_f32_e32 v159, v159
	s_nop 0
	v_mul_f32_e32 v158, v64, v158
	v_mul_f32_e32 v159, v65, v159
	v_cvt_pk_bf16_f32 v203, v158, v159
	global_store_dwordx4 v[248:249], v[200:203], off
	s_waitcnt vmcnt(15)
	v_lshlrev_b32_e32 v138, 16, v204
	v_and_b32_e32 v139, 0xffff0000, v204
	v_rcp_f32_e32 v138, v138
	v_rcp_f32_e32 v139, v139
	s_nop 0
	v_mul_f32_e32 v138, v34, v138
	v_mul_f32_e32 v139, v35, v139
	v_cvt_pk_bf16_f32 v204, v138, v139
	v_lshlrev_b32_e32 v158, 16, v205
	v_and_b32_e32 v159, 0xffff0000, v205
	v_rcp_f32_e32 v158, v158
	v_rcp_f32_e32 v159, v159
	s_nop 0
	v_mul_f32_e32 v158, v36, v158
	v_mul_f32_e32 v159, v37, v159
	v_cvt_pk_bf16_f32 v205, v158, v159
	v_lshlrev_b32_e32 v138, 16, v206
	v_and_b32_e32 v139, 0xffff0000, v206
	v_rcp_f32_e32 v138, v138
	v_rcp_f32_e32 v139, v139
	s_nop 0
	v_mul_f32_e32 v138, v30, v138
	v_mul_f32_e32 v139, v31, v139
	v_cvt_pk_bf16_f32 v206, v138, v139
	v_lshlrev_b32_e32 v158, 16, v207
	v_and_b32_e32 v159, 0xffff0000, v207
	v_rcp_f32_e32 v158, v158
	v_rcp_f32_e32 v159, v159
	s_nop 0
	v_mul_f32_e32 v158, v32, v158
	v_mul_f32_e32 v159, v33, v159
	v_cvt_pk_bf16_f32 v207, v158, v159
	global_store_dwordx4 v[248:249], v[204:207], off offset:256
	v_add_co_u32_e32 v248, vcc, 0x8000, v248
	s_nop 1
	v_addc_co_u32_e32 v249, vcc, 0, v249, vcc
	s_waitcnt vmcnt(15)
	v_lshlrev_b32_e32 v138, 16, v208
	v_and_b32_e32 v139, 0xffff0000, v208
	v_rcp_f32_e32 v138, v138
	v_rcp_f32_e32 v139, v139
	s_nop 0
	v_mul_f32_e32 v138, v58, v138
	v_mul_f32_e32 v139, v59, v139
	v_cvt_pk_bf16_f32 v208, v138, v139
	v_lshlrev_b32_e32 v158, 16, v209
	v_and_b32_e32 v159, 0xffff0000, v209
	v_rcp_f32_e32 v158, v158
	v_rcp_f32_e32 v159, v159
	s_nop 0
	v_mul_f32_e32 v158, v60, v158
	v_mul_f32_e32 v159, v61, v159
	v_cvt_pk_bf16_f32 v209, v158, v159
	v_lshlrev_b32_e32 v138, 16, v210
	v_and_b32_e32 v139, 0xffff0000, v210
	v_rcp_f32_e32 v138, v138
	v_rcp_f32_e32 v139, v139
	s_nop 0
	v_mul_f32_e32 v138, v54, v138
	v_mul_f32_e32 v139, v55, v139
	v_cvt_pk_bf16_f32 v210, v138, v139
	v_lshlrev_b32_e32 v158, 16, v211
	v_and_b32_e32 v159, 0xffff0000, v211
	v_rcp_f32_e32 v158, v158
	v_rcp_f32_e32 v159, v159
	s_nop 0
	v_mul_f32_e32 v158, v56, v158
	v_mul_f32_e32 v159, v57, v159
	v_cvt_pk_bf16_f32 v211, v158, v159
	global_store_dwordx4 v[248:249], v[208:211], off
	s_waitcnt vmcnt(15)
	v_lshlrev_b32_e32 v138, 16, v212
	v_and_b32_e32 v139, 0xffff0000, v212
	v_rcp_f32_e32 v138, v138
	v_rcp_f32_e32 v139, v139
	s_nop 0
	v_mul_f32_e32 v138, v26, v138
	v_mul_f32_e32 v139, v27, v139
	v_cvt_pk_bf16_f32 v212, v138, v139
	v_lshlrev_b32_e32 v158, 16, v213
	v_and_b32_e32 v159, 0xffff0000, v213
	v_rcp_f32_e32 v158, v158
	v_rcp_f32_e32 v159, v159
	s_nop 0
	v_mul_f32_e32 v158, v28, v158
	v_mul_f32_e32 v159, v29, v159
	v_cvt_pk_bf16_f32 v213, v158, v159
	v_lshlrev_b32_e32 v138, 16, v214
	v_and_b32_e32 v139, 0xffff0000, v214
	v_rcp_f32_e32 v138, v138
	v_rcp_f32_e32 v139, v139
	s_nop 0
	v_mul_f32_e32 v138, v22, v138
	v_mul_f32_e32 v139, v23, v139
	v_cvt_pk_bf16_f32 v214, v138, v139
	v_lshlrev_b32_e32 v158, 16, v215
	v_and_b32_e32 v159, 0xffff0000, v215
	v_rcp_f32_e32 v158, v158
	v_rcp_f32_e32 v159, v159
	s_nop 0
	v_mul_f32_e32 v158, v24, v158
	v_mul_f32_e32 v159, v25, v159
	v_cvt_pk_bf16_f32 v215, v158, v159
	global_store_dwordx4 v[248:249], v[212:215], off offset:256
	v_add_co_u32_e32 v248, vcc, 0x8000, v248
	s_nop 1
	v_addc_co_u32_e32 v249, vcc, 0, v249, vcc
	s_waitcnt vmcnt(15)
	v_lshlrev_b32_e32 v138, 16, v220
	v_and_b32_e32 v139, 0xffff0000, v220
	v_rcp_f32_e32 v138, v138
	v_rcp_f32_e32 v139, v139
	s_nop 0
	v_mul_f32_e32 v138, v50, v138
	v_mul_f32_e32 v139, v51, v139
	v_cvt_pk_bf16_f32 v220, v138, v139
	v_lshlrev_b32_e32 v158, 16, v221
	v_and_b32_e32 v159, 0xffff0000, v221
	v_rcp_f32_e32 v158, v158
	v_rcp_f32_e32 v159, v159
	s_nop 0
	v_mul_f32_e32 v158, v52, v158
	v_mul_f32_e32 v159, v53, v159
	v_cvt_pk_bf16_f32 v221, v158, v159
	v_lshlrev_b32_e32 v138, 16, v222
	v_and_b32_e32 v139, 0xffff0000, v222
	v_rcp_f32_e32 v138, v138
	v_rcp_f32_e32 v139, v139
	s_nop 0
	v_mul_f32_e32 v138, v46, v138
	v_mul_f32_e32 v139, v47, v139
	v_cvt_pk_bf16_f32 v222, v138, v139
	v_lshlrev_b32_e32 v158, 16, v223
	v_and_b32_e32 v159, 0xffff0000, v223
	v_rcp_f32_e32 v158, v158
	v_rcp_f32_e32 v159, v159
	s_nop 0
	v_mul_f32_e32 v158, v48, v158
	v_mul_f32_e32 v159, v49, v159
	v_cvt_pk_bf16_f32 v223, v158, v159
	global_store_dwordx4 v[248:249], v[220:223], off
	s_waitcnt vmcnt(15)
	v_lshlrev_b32_e32 v138, 16, v228
	v_and_b32_e32 v139, 0xffff0000, v228
	v_rcp_f32_e32 v138, v138
	v_rcp_f32_e32 v139, v139
	s_nop 0
	v_mul_f32_e32 v138, v18, v138
	v_mul_f32_e32 v139, v19, v139
	v_cvt_pk_bf16_f32 v228, v138, v139
	v_lshlrev_b32_e32 v158, 16, v229
	v_and_b32_e32 v159, 0xffff0000, v229
	v_rcp_f32_e32 v158, v158
	v_rcp_f32_e32 v159, v159
	s_nop 0
	v_mul_f32_e32 v158, v20, v158
	v_mul_f32_e32 v159, v21, v159
	v_cvt_pk_bf16_f32 v229, v158, v159
	v_lshlrev_b32_e32 v138, 16, v230
	v_and_b32_e32 v139, 0xffff0000, v230
	v_rcp_f32_e32 v138, v138
	v_rcp_f32_e32 v139, v139
	s_nop 0
	v_mul_f32_e32 v138, v14, v138
	v_mul_f32_e32 v139, v15, v139
	v_cvt_pk_bf16_f32 v230, v138, v139
	v_lshlrev_b32_e32 v158, 16, v231
	v_and_b32_e32 v159, 0xffff0000, v231
	v_rcp_f32_e32 v158, v158
	v_rcp_f32_e32 v159, v159
	s_nop 0
	v_mul_f32_e32 v158, v16, v158
	v_mul_f32_e32 v159, v17, v159
	v_cvt_pk_bf16_f32 v231, v158, v159
	global_store_dwordx4 v[248:249], v[228:231], off offset:256
	v_add_co_u32_e32 v248, vcc, 0x8000, v248
	s_nop 1
	v_addc_co_u32_e32 v249, vcc, 0, v249, vcc
	s_waitcnt vmcnt(15)
	v_lshlrev_b32_e32 v138, 16, v232
	v_and_b32_e32 v139, 0xffff0000, v232
	v_rcp_f32_e32 v138, v138
	v_rcp_f32_e32 v139, v139
	s_nop 0
	v_mul_f32_e32 v138, v42, v138
	v_mul_f32_e32 v139, v43, v139
	v_cvt_pk_bf16_f32 v232, v138, v139
	v_lshlrev_b32_e32 v158, 16, v233
	v_and_b32_e32 v159, 0xffff0000, v233
	v_rcp_f32_e32 v158, v158
	v_rcp_f32_e32 v159, v159
	s_nop 0
	v_mul_f32_e32 v158, v44, v158
	v_mul_f32_e32 v159, v45, v159
	v_cvt_pk_bf16_f32 v233, v158, v159
	v_lshlrev_b32_e32 v138, 16, v234
	v_and_b32_e32 v139, 0xffff0000, v234
	v_rcp_f32_e32 v138, v138
	v_rcp_f32_e32 v139, v139
	s_nop 0
	v_mul_f32_e32 v138, v38, v138
	v_mul_f32_e32 v139, v39, v139
	v_cvt_pk_bf16_f32 v234, v138, v139
	v_lshlrev_b32_e32 v158, 16, v235
	v_and_b32_e32 v159, 0xffff0000, v235
	v_rcp_f32_e32 v158, v158
	v_rcp_f32_e32 v159, v159
	s_nop 0
	v_mul_f32_e32 v158, v40, v158
	v_mul_f32_e32 v159, v41, v159
	v_cvt_pk_bf16_f32 v235, v158, v159
	global_store_dwordx4 v[248:249], v[232:235], off
	s_waitcnt vmcnt(15)
	v_lshlrev_b32_e32 v138, 16, v236
	v_and_b32_e32 v139, 0xffff0000, v236
	v_rcp_f32_e32 v138, v138
	v_rcp_f32_e32 v139, v139
	s_nop 0
	v_mul_f32_e32 v138, v10, v138
	v_mul_f32_e32 v139, v11, v139
	v_cvt_pk_bf16_f32 v236, v138, v139
	v_lshlrev_b32_e32 v158, 16, v237
	v_and_b32_e32 v159, 0xffff0000, v237
	v_rcp_f32_e32 v158, v158
	v_rcp_f32_e32 v159, v159
	s_nop 0
	v_mul_f32_e32 v158, v12, v158
	v_mul_f32_e32 v159, v13, v159
	v_cvt_pk_bf16_f32 v237, v158, v159
	v_lshlrev_b32_e32 v138, 16, v238
	v_and_b32_e32 v139, 0xffff0000, v238
	v_rcp_f32_e32 v138, v138
	v_rcp_f32_e32 v139, v139
	s_nop 0
	v_mul_f32_e32 v138, v6, v138
	v_mul_f32_e32 v139, v7, v139
	v_cvt_pk_bf16_f32 v238, v138, v139
	v_lshlrev_b32_e32 v158, 16, v239
	v_and_b32_e32 v159, 0xffff0000, v239
	v_rcp_f32_e32 v158, v158
	v_rcp_f32_e32 v159, v159
	s_nop 0
	v_mul_f32_e32 v158, v8, v158
	v_mul_f32_e32 v159, v9, v159
	v_cvt_pk_bf16_f32 v239, v158, v159
	global_store_dwordx4 v[248:249], v[236:239], off offset:256
	s_branch .LBB0_778
.Lepi2_z0:
	s_nop 7
	s_nop 7
	v_mov_b64_e32 v[180:181], v[4:5]
	global_load_dwordx4 v[168:171], v[180:181], off
	global_load_dwordx4 v[172:175], v[180:181], off offset:2048
	global_load_dwordx4 v[176:179], v[180:181], off offset:256
	global_load_dwordx4 v[180:183], v[180:181], off offset:2304
	v_add_co_u32_e32 v196, vcc, 0x10000, v4
	s_nop 1
	v_addc_co_u32_e32 v197, vcc, 0, v5, vcc
	global_load_dwordx4 v[184:187], v[196:197], off
	global_load_dwordx4 v[188:191], v[196:197], off offset:2048
	global_load_dwordx4 v[192:195], v[196:197], off offset:256
	global_load_dwordx4 v[196:199], v[196:197], off offset:2304
	v_add_co_u32_e32 v212, vcc, 0x20000, v4
	s_nop 1
	v_addc_co_u32_e32 v213, vcc, 0, v5, vcc
	global_load_dwordx4 v[200:203], v[212:213], off
	global_load_dwordx4 v[204:207], v[212:213], off offset:2048
	global_load_dwordx4 v[208:211], v[212:213], off offset:256
	global_load_dwordx4 v[212:215], v[212:213], off offset:2304
	v_add_co_u32_e32 v236, vcc, 0x30000, v4
	s_nop 1
	v_addc_co_u32_e32 v237, vcc, 0, v5, vcc
	global_load_dwordx4 v[220:223], v[236:237], off
	global_load_dwordx4 v[228:231], v[236:237], off offset:2048
	global_load_dwordx4 v[232:235], v[236:237], off offset:256
	global_load_dwordx4 v[236:239], v[236:237], off offset:2304
	v_add_co_u32_e32 v134, vcc, 0x80000, v4
	s_nop 1
	v_addc_co_u32_e32 v135, vcc, 0, v5, vcc
	global_load_dwordx4 v[240:243], v[134:135], off
	global_load_dwordx4 v[244:247], v[134:135], off offset:2048
	global_load_dwordx4 v[252:255], v[134:135], off offset:256
	global_load_dwordx4 v[134:137], v[134:135], off offset:2304
	s_waitcnt vmcnt(18)
	v_lshlrev_b32_e32 v138, 16, v168
	v_and_b32_e32 v139, 0xffff0000, v168
	v_lshlrev_b32_e32 v140, 16, v172
	v_and_b32_e32 v141, 0xffff0000, v172
	v_pk_mul_f32 v[138:139], v[138:139], v[140:141]
	v_pk_mul_f32 v[130:131], v[130:131], v[138:139]
	v_lshlrev_b32_e32 v158, 16, v169
	v_and_b32_e32 v159, 0xffff0000, v169
	v_lshlrev_b32_e32 v160, 16, v173
	v_and_b32_e32 v161, 0xffff0000, v173
	v_pk_mul_f32 v[158:159], v[158:159], v[160:161]
	v_pk_mul_f32 v[132:133], v[132:133], v[158:159]
	v_lshlrev_b32_e32 v138, 16, v170
	v_and_b32_e32 v139, 0xffff0000, v170
	v_lshlrev_b32_e32 v140, 16, v174
	v_and_b32_e32 v141, 0xffff0000, v174
	v_pk_mul_f32 v[138:139], v[138:139], v[140:141]
	v_pk_mul_f32 v[126:127], v[126:127], v[138:139]
	v_lshlrev_b32_e32 v158, 16, v171
	v_and_b32_e32 v159, 0xffff0000, v171
	v_lshlrev_b32_e32 v160, 16, v175
	v_and_b32_e32 v161, 0xffff0000, v175
	v_pk_mul_f32 v[158:159], v[158:159], v[160:161]
	v_pk_mul_f32 v[128:129], v[128:129], v[158:159]
	s_waitcnt vmcnt(16)
	v_lshlrev_b32_e32 v138, 16, v176
	v_and_b32_e32 v139, 0xffff0000, v176
	v_lshlrev_b32_e32 v140, 16, v180
	v_and_b32_e32 v141, 0xffff0000, v180
	v_pk_mul_f32 v[138:139], v[138:139], v[140:141]
	v_pk_mul_f32 v[98:99], v[98:99], v[138:139]
	v_lshlrev_b32_e32 v158, 16, v177
	v_and_b32_e32 v159, 0xffff0000, v177
	v_lshlrev_b32_e32 v160, 16, v181
	v_and_b32_e32 v161, 0xffff0000, v181
	v_pk_mul_f32 v[158:159], v[158:159], v[160:161]
	v_pk_mul_f32 v[100:101], v[100:101], v[158:159]
	v_lshlrev_b32_e32 v138, 16, v178
	v_and_b32_e32 v139, 0xffff0000, v178
	v_lshlrev_b32_e32 v140, 16, v182
	v_and_b32_e32 v141, 0xffff0000, v182
	v_pk_mul_f32 v[138:139], v[138:139], v[140:141]
	v_pk_mul_f32 v[94:95], v[94:95], v[138:139]
	v_lshlrev_b32_e32 v158, 16, v179
	v_and_b32_e32 v159, 0xffff0000, v179
	v_lshlrev_b32_e32 v160, 16, v183
	v_and_b32_e32 v161, 0xffff0000, v183
	v_pk_mul_f32 v[158:159], v[158:159], v[160:161]
	v_pk_mul_f32 v[96:97], v[96:97], v[158:159]
	v_add_co_u32_e32 v180, vcc, 0x90000, v4
	s_nop 1
	v_addc_co_u32_e32 v181, vcc, 0, v5, vcc
	global_load_dwordx4 v[168:171], v[180:181], off
	global_load_dwordx4 v[172:175], v[180:181], off offset:2048
	global_load_dwordx4 v[176:179], v[180:181], off offset:256
	global_load_dwordx4 v[180:183], v[180:181], off offset:2304
	s_waitcnt vmcnt(18)
	v_lshlrev_b32_e32 v138, 16, v184
	v_and_b32_e32 v139, 0xffff0000, v184
	v_lshlrev_b32_e32 v140, 16, v188
	v_and_b32_e32 v141, 0xffff0000, v188
	v_pk_mul_f32 v[138:139], v[138:139], v[140:141]
	v_pk_mul_f32 v[122:123], v[122:123], v[138:139]
	v_lshlrev_b32_e32 v158, 16, v185
	v_and_b32_e32 v159, 0xffff0000, v185
	v_lshlrev_b32_e32 v160, 16, v189
	v_and_b32_e32 v161, 0xffff0000, v189
	v_pk_mul_f32 v[158:159], v[158:159], v[160:161]
	v_pk_mul_f32 v[124:125], v[124:125], v[158:159]
	v_lshlrev_b32_e32 v138, 16, v186
	v_and_b32_e32 v139, 0xffff0000, v186
	v_lshlrev_b32_e32 v140, 16, v190
	v_and_b32_e32 v141, 0xffff0000, v190
	v_pk_mul_f32 v[138:139], v[138:139], v[140:141]
	v_pk_mul_f32 v[118:119], v[118:119], v[138:139]
	v_lshlrev_b32_e32 v158, 16, v187
	v_and_b32_e32 v159, 0xffff0000, v187
	v_lshlrev_b32_e32 v160, 16, v191
	v_and_b32_e32 v161, 0xffff0000, v191
	v_pk_mul_f32 v[158:159], v[158:159], v[160:161]
	v_pk_mul_f32 v[120:121], v[120:121], v[158:159]
	s_waitcnt vmcnt(16)
	v_lshlrev_b32_e32 v138, 16, v192
	v_and_b32_e32 v139, 0xffff0000, v192
	v_lshlrev_b32_e32 v140, 16, v196
	v_and_b32_e32 v141, 0xffff0000, v196
	v_pk_mul_f32 v[138:139], v[138:139], v[140:141]
	v_pk_mul_f32 v[90:91], v[90:91], v[138:139]
	v_lshlrev_b32_e32 v158, 16, v193
	v_and_b32_e32 v159, 0xffff0000, v193
	v_lshlrev_b32_e32 v160, 16, v197
	v_and_b32_e32 v161, 0xffff0000, v197
	v_pk_mul_f32 v[158:159], v[158:159], v[160:161]
	v_pk_mul_f32 v[92:93], v[92:93], v[158:159]
	v_lshlrev_b32_e32 v138, 16, v194
	v_and_b32_e32 v139, 0xffff0000, v194
	v_lshlrev_b32_e32 v140, 16, v198
	v_and_b32_e32 v141, 0xffff0000, v198
	v_pk_mul_f32 v[138:139], v[138:139], v[140:141]
	v_pk_mul_f32 v[86:87], v[86:87], v[138:139]
	v_lshlrev_b32_e32 v158, 16, v195
	v_and_b32_e32 v159, 0xffff0000, v195
	v_lshlrev_b32_e32 v160, 16, v199
	v_and_b32_e32 v161, 0xffff0000, v199
	v_pk_mul_f32 v[158:159], v[158:159], v[160:161]
	v_pk_mul_f32 v[88:89], v[88:89], v[158:159]
	v_add_co_u32_e32 v196, vcc, 0xa0000, v4
	s_nop 1
	v_addc_co_u32_e32 v197, vcc, 0, v5, vcc
	global_load_dwordx4 v[184:187], v[196:197], off
	global_load_dwordx4 v[188:191], v[196:197], off offset:2048
	global_load_dwordx4 v[192:195], v[196:197], off offset:256
	global_load_dwordx4 v[196:199], v[196:197], off offset:2304
	s_waitcnt vmcnt(18)
	v_lshlrev_b32_e32 v138, 16, v200
	v_and_b32_e32 v139, 0xffff0000, v200
	v_lshlrev_b32_e32 v140, 16, v204
	v_and_b32_e32 v141, 0xffff0000, v204
	v_pk_mul_f32 v[138:139], v[138:139], v[140:141]
	v_pk_mul_f32 v[114:115], v[114:115], v[138:139]
	v_lshlrev_b32_e32 v158, 16, v201
	v_and_b32_e32 v159, 0xffff0000, v201
	v_lshlrev_b32_e32 v160, 16, v205
	v_and_b32_e32 v161, 0xffff0000, v205
	v_pk_mul_f32 v[158:159], v[158:159], v[160:161]
	v_pk_mul_f32 v[116:117], v[116:117], v[158:159]
	v_lshlrev_b32_e32 v138, 16, v202
	v_and_b32_e32 v139, 0xffff0000, v202
	v_lshlrev_b32_e32 v140, 16, v206
	v_and_b32_e32 v141, 0xffff0000, v206
	v_pk_mul_f32 v[138:139], v[138:139], v[140:141]
	v_pk_mul_f32 v[110:111], v[110:111], v[138:139]
	v_lshlrev_b32_e32 v158, 16, v203
	v_and_b32_e32 v159, 0xffff0000, v203
	v_lshlrev_b32_e32 v160, 16, v207
	v_and_b32_e32 v161, 0xffff0000, v207
	v_pk_mul_f32 v[158:159], v[158:159], v[160:161]
	v_pk_mul_f32 v[112:113], v[112:113], v[158:159]
	s_waitcnt vmcnt(16)
	v_lshlrev_b32_e32 v138, 16, v208
	v_and_b32_e32 v139, 0xffff0000, v208
	v_lshlrev_b32_e32 v140, 16, v212
	v_and_b32_e32 v141, 0xffff0000, v212
	v_pk_mul_f32 v[138:139], v[138:139], v[140:141]
	v_pk_mul_f32 v[82:83], v[82:83], v[138:139]
	v_lshlrev_b32_e32 v158, 16, v209
	v_and_b32_e32 v159, 0xffff0000, v209
	v_lshlrev_b32_e32 v160, 16, v213
	v_and_b32_e32 v161, 0xffff0000, v213
	v_pk_mul_f32 v[158:159], v[158:159], v[160:161]
	v_pk_mul_f32 v[84:85], v[84:85], v[158:159]
	v_lshlrev_b32_e32 v138, 16, v210
	v_and_b32_e32 v139, 0xffff0000, v210
	v_lshlrev_b32_e32 v140, 16, v214
	v_and_b32_e32 v141, 0xffff0000, v214
	v_pk_mul_f32 v[138:139], v[138:139], v[140:141]
	v_pk_mul_f32 v[78:79], v[78:79], v[138:139]
	v_lshlrev_b32_e32 v158, 16, v211
	v_and_b32_e32 v159, 0xffff0000, v211
	v_lshlrev_b32_e32 v160, 16, v215
	v_and_b32_e32 v161, 0xffff0000, v215
	v_pk_mul_f32 v[158:159], v[158:159], v[160:161]
	v_pk_mul_f32 v[80:81], v[80:81], v[158:159]
	v_add_co_u32_e32 v212, vcc, 0xb0000, v4
	s_nop 1
	v_addc_co_u32_e32 v213, vcc, 0, v5, vcc
	global_load_dwordx4 v[200:203], v[212:213], off
	global_load_dwordx4 v[204:207], v[212:213], off offset:2048
	global_load_dwordx4 v[208:211], v[212:213], off offset:256
	global_load_dwordx4 v[212:215], v[212:213], off offset:2304
	s_waitcnt vmcnt(18)
	v_lshlrev_b32_e32 v138, 16, v220
	v_and_b32_e32 v139, 0xffff0000, v220
	v_lshlrev_b32_e32 v140, 16, v228
	v_and_b32_e32 v141, 0xffff0000, v228
	v_pk_mul_f32 v[138:139], v[138:139], v[140:141]
	v_pk_mul_f32 v[106:107], v[106:107], v[138:139]
	v_lshlrev_b32_e32 v158, 16, v221
	v_and_b32_e32 v159, 0xffff0000, v221
	v_lshlrev_b32_e32 v160, 16, v229
	v_and_b32_e32 v161, 0xffff0000, v229
	v_pk_mul_f32 v[158:159], v[158:159], v[160:161]
	v_pk_mul_f32 v[108:109], v[108:109], v[158:159]
	v_lshlrev_b32_e32 v138, 16, v222
	v_and_b32_e32 v139, 0xffff0000, v222
	v_lshlrev_b32_e32 v140, 16, v230
	v_and_b32_e32 v141, 0xffff0000, v230
	v_pk_mul_f32 v[138:139], v[138:139], v[140:141]
	v_pk_mul_f32 v[102:103], v[102:103], v[138:139]
	v_lshlrev_b32_e32 v158, 16, v223
	v_and_b32_e32 v159, 0xffff0000, v223
	v_lshlrev_b32_e32 v160, 16, v231
	v_and_b32_e32 v161, 0xffff0000, v231
	v_pk_mul_f32 v[158:159], v[158:159], v[160:161]
	v_pk_mul_f32 v[104:105], v[104:105], v[158:159]
	s_waitcnt vmcnt(16)
	v_lshlrev_b32_e32 v138, 16, v232
	v_and_b32_e32 v139, 0xffff0000, v232
	v_lshlrev_b32_e32 v140, 16, v236
	v_and_b32_e32 v141, 0xffff0000, v236
	v_pk_mul_f32 v[138:139], v[138:139], v[140:141]
	v_pk_mul_f32 v[74:75], v[74:75], v[138:139]
	v_lshlrev_b32_e32 v158, 16, v233
	v_and_b32_e32 v159, 0xffff0000, v233
	v_lshlrev_b32_e32 v160, 16, v237
	v_and_b32_e32 v161, 0xffff0000, v237
	v_pk_mul_f32 v[158:159], v[158:159], v[160:161]
	v_pk_mul_f32 v[76:77], v[76:77], v[158:159]
	v_lshlrev_b32_e32 v138, 16, v234
	v_and_b32_e32 v139, 0xffff0000, v234
	v_lshlrev_b32_e32 v140, 16, v238
	v_and_b32_e32 v141, 0xffff0000, v238
	v_pk_mul_f32 v[138:139], v[138:139], v[140:141]
	v_pk_mul_f32 v[70:71], v[70:71], v[138:139]
	v_lshlrev_b32_e32 v158, 16, v235
	v_and_b32_e32 v159, 0xffff0000, v235
	v_lshlrev_b32_e32 v160, 16, v239
	v_and_b32_e32 v161, 0xffff0000, v239
	v_pk_mul_f32 v[158:159], v[158:159], v[160:161]
	v_pk_mul_f32 v[72:73], v[72:73], v[158:159]
	s_waitcnt vmcnt(14)
	v_lshlrev_b32_e32 v138, 16, v240
	v_and_b32_e32 v139, 0xffff0000, v240
	v_lshlrev_b32_e32 v140, 16, v244
	v_and_b32_e32 v141, 0xffff0000, v244
	v_pk_mul_f32 v[138:139], v[138:139], v[140:141]
	v_pk_mul_f32 v[66:67], v[66:67], v[138:139]
	v_lshlrev_b32_e32 v158, 16, v241
	v_and_b32_e32 v159, 0xffff0000, v241
	v_lshlrev_b32_e32 v160, 16, v245
	v_and_b32_e32 v161, 0xffff0000, v245
	v_pk_mul_f32 v[158:159], v[158:159], v[160:161]
	v_pk_mul_f32 v[68:69], v[68:69], v[158:159]
	v_lshlrev_b32_e32 v138, 16, v242
	v_and_b32_e32 v139, 0xffff0000, v242
	v_lshlrev_b32_e32 v140, 16, v246
	v_and_b32_e32 v141, 0xffff0000, v246
	v_pk_mul_f32 v[138:139], v[138:139], v[140:141]
	v_pk_mul_f32 v[62:63], v[62:63], v[138:139]
	v_lshlrev_b32_e32 v158, 16, v243
	v_and_b32_e32 v159, 0xffff0000, v243
	v_lshlrev_b32_e32 v160, 16, v247
	v_and_b32_e32 v161, 0xffff0000, v247
	v_pk_mul_f32 v[158:159], v[158:159], v[160:161]
	v_pk_mul_f32 v[64:65], v[64:65], v[158:159]
	s_waitcnt vmcnt(12)
	v_lshlrev_b32_e32 v138, 16, v252
	v_and_b32_e32 v139, 0xffff0000, v252
	v_lshlrev_b32_e32 v140, 16, v134
	v_and_b32_e32 v141, 0xffff0000, v134
	v_pk_mul_f32 v[138:139], v[138:139], v[140:141]
	v_pk_mul_f32 v[34:35], v[34:35], v[138:139]
	v_lshlrev_b32_e32 v158, 16, v253
	v_and_b32_e32 v159, 0xffff0000, v253
	v_lshlrev_b32_e32 v160, 16, v135
	v_and_b32_e32 v161, 0xffff0000, v135
	v_pk_mul_f32 v[158:159], v[158:159], v[160:161]
	v_pk_mul_f32 v[36:37], v[36:37], v[158:159]
	v_lshlrev_b32_e32 v138, 16, v254
	v_and_b32_e32 v139, 0xffff0000, v254
	v_lshlrev_b32_e32 v140, 16, v136
	v_and_b32_e32 v141, 0xffff0000, v136
	v_pk_mul_f32 v[138:139], v[138:139], v[140:141]
	v_pk_mul_f32 v[30:31], v[30:31], v[138:139]
	v_lshlrev_b32_e32 v158, 16, v255
	v_and_b32_e32 v159, 0xffff0000, v255
	v_lshlrev_b32_e32 v160, 16, v137
	v_and_b32_e32 v161, 0xffff0000, v137
	v_pk_mul_f32 v[158:159], v[158:159], v[160:161]
	v_pk_mul_f32 v[32:33], v[32:33], v[158:159]
	s_waitcnt vmcnt(10)
	v_lshlrev_b32_e32 v138, 16, v168
	v_and_b32_e32 v139, 0xffff0000, v168
	v_lshlrev_b32_e32 v140, 16, v172
	v_and_b32_e32 v141, 0xffff0000, v172
	v_pk_mul_f32 v[138:139], v[138:139], v[140:141]
	v_pk_mul_f32 v[58:59], v[58:59], v[138:139]
	v_lshlrev_b32_e32 v158, 16, v169
	v_and_b32_e32 v159, 0xffff0000, v169
	v_lshlrev_b32_e32 v160, 16, v173
	v_and_b32_e32 v161, 0xffff0000, v173
	v_pk_mul_f32 v[158:159], v[158:159], v[160:161]
	v_pk_mul_f32 v[60:61], v[60:61], v[158:159]
	v_lshlrev_b32_e32 v138, 16, v170
	v_and_b32_e32 v139, 0xffff0000, v170
	v_lshlrev_b32_e32 v140, 16, v174
	v_and_b32_e32 v141, 0xffff0000, v174
	v_pk_mul_f32 v[138:139], v[138:139], v[140:141]
	v_pk_mul_f32 v[54:55], v[54:55], v[138:139]
	v_lshlrev_b32_e32 v158, 16, v171
	v_and_b32_e32 v159, 0xffff0000, v171
	v_lshlrev_b32_e32 v160, 16, v175
	v_and_b32_e32 v161, 0xffff0000, v175
	v_pk_mul_f32 v[158:159], v[158:159], v[160:161]
	v_pk_mul_f32 v[56:57], v[56:57], v[158:159]
	s_waitcnt vmcnt(8)
	v_lshlrev_b32_e32 v138, 16, v176
	v_and_b32_e32 v139, 0xffff0000, v176
	v_lshlrev_b32_e32 v140, 16, v180
	v_and_b32_e32 v141, 0xffff0000, v180
	v_pk_mul_f32 v[138:139], v[138:139], v[140:141]
	v_pk_mul_f32 v[26:27], v[26:27], v[138:139]
	v_lshlrev_b32_e32 v158, 16, v177
	v_and_b32_e32 v159, 0xffff0000, v177
	v_lshlrev_b32_e32 v160, 16, v181
	v_and_b32_e32 v161, 0xffff0000, v181
	v_pk_mul_f32 v[158:159], v[158:159], v[160:161]
	v_pk_mul_f32 v[28:29], v[28:29], v[158:159]
	v_lshlrev_b32_e32 v138, 16, v178
	v_and_b32_e32 v139, 0xffff0000, v178
	v_lshlrev_b32_e32 v140, 16, v182
	v_and_b32_e32 v141, 0xffff0000, v182
	v_pk_mul_f32 v[138:139], v[138:139], v[140:141]
	v_pk_mul_f32 v[22:23], v[22:23], v[138:139]
	v_lshlrev_b32_e32 v158, 16, v179
	v_and_b32_e32 v159, 0xffff0000, v179
	v_lshlrev_b32_e32 v160, 16, v183
	v_and_b32_e32 v161, 0xffff0000, v183
	v_pk_mul_f32 v[158:159], v[158:159], v[160:161]
	v_pk_mul_f32 v[24:25], v[24:25], v[158:159]
	s_waitcnt vmcnt(6)
	v_lshlrev_b32_e32 v138, 16, v184
	v_and_b32_e32 v139, 0xffff0000, v184
	v_lshlrev_b32_e32 v140, 16, v188
	v_and_b32_e32 v141, 0xffff0000, v188
	v_pk_mul_f32 v[138:139], v[138:139], v[140:141]
	v_pk_mul_f32 v[50:51], v[50:51], v[138:139]
	v_lshlrev_b32_e32 v158, 16, v185
	v_and_b32_e32 v159, 0xffff0000, v185
	v_lshlrev_b32_e32 v160, 16, v189
	v_and_b32_e32 v161, 0xffff0000, v189
	v_pk_mul_f32 v[158:159], v[158:159], v[160:161]
	v_pk_mul_f32 v[52:53], v[52:53], v[158:159]
	v_lshlrev_b32_e32 v138, 16, v186
	v_and_b32_e32 v139, 0xffff0000, v186
	v_lshlrev_b32_e32 v140, 16, v190
	v_and_b32_e32 v141, 0xffff0000, v190
	v_pk_mul_f32 v[138:139], v[138:139], v[140:141]
	v_pk_mul_f32 v[46:47], v[46:47], v[138:139]
	v_lshlrev_b32_e32 v158, 16, v187
	v_and_b32_e32 v159, 0xffff0000, v187
	v_lshlrev_b32_e32 v160, 16, v191
	v_and_b32_e32 v161, 0xffff0000, v191
	v_pk_mul_f32 v[158:159], v[158:159], v[160:161]
	v_pk_mul_f32 v[48:49], v[48:49], v[158:159]
	s_waitcnt vmcnt(4)
	v_lshlrev_b32_e32 v138, 16, v192
	v_and_b32_e32 v139, 0xffff0000, v192
	v_lshlrev_b32_e32 v140, 16, v196
	v_and_b32_e32 v141, 0xffff0000, v196
	v_pk_mul_f32 v[138:139], v[138:139], v[140:141]
	v_pk_mul_f32 v[18:19], v[18:19], v[138:139]
	v_lshlrev_b32_e32 v158, 16, v193
	v_and_b32_e32 v159, 0xffff0000, v193
	v_lshlrev_b32_e32 v160, 16, v197
	v_and_b32_e32 v161, 0xffff0000, v197
	v_pk_mul_f32 v[158:159], v[158:159], v[160:161]
	v_pk_mul_f32 v[20:21], v[20:21], v[158:159]
	v_lshlrev_b32_e32 v138, 16, v194
	v_and_b32_e32 v139, 0xffff0000, v194
	v_lshlrev_b32_e32 v140, 16, v198
	v_and_b32_e32 v141, 0xffff0000, v198
	v_pk_mul_f32 v[138:139], v[138:139], v[140:141]
	v_pk_mul_f32 v[14:15], v[14:15], v[138:139]
	v_lshlrev_b32_e32 v158, 16, v195
	v_and_b32_e32 v159, 0xffff0000, v195
	v_lshlrev_b32_e32 v160, 16, v199
	v_and_b32_e32 v161, 0xffff0000, v199
	v_pk_mul_f32 v[158:159], v[158:159], v[160:161]
	v_pk_mul_f32 v[16:17], v[16:17], v[158:159]
	s_waitcnt vmcnt(2)
	v_lshlrev_b32_e32 v138, 16, v200
	v_and_b32_e32 v139, 0xffff0000, v200
	v_lshlrev_b32_e32 v140, 16, v204
	v_and_b32_e32 v141, 0xffff0000, v204
	v_pk_mul_f32 v[138:139], v[138:139], v[140:141]
	v_pk_mul_f32 v[42:43], v[42:43], v[138:139]
	v_lshlrev_b32_e32 v158, 16, v201
	v_and_b32_e32 v159, 0xffff0000, v201
	v_lshlrev_b32_e32 v160, 16, v205
	v_and_b32_e32 v161, 0xffff0000, v205
	v_pk_mul_f32 v[158:159], v[158:159], v[160:161]
	v_pk_mul_f32 v[44:45], v[44:45], v[158:159]
	v_lshlrev_b32_e32 v138, 16, v202
	v_and_b32_e32 v139, 0xffff0000, v202
	v_lshlrev_b32_e32 v140, 16, v206
	v_and_b32_e32 v141, 0xffff0000, v206
	v_pk_mul_f32 v[138:139], v[138:139], v[140:141]
	v_pk_mul_f32 v[38:39], v[38:39], v[138:139]
	v_lshlrev_b32_e32 v158, 16, v203
	v_and_b32_e32 v159, 0xffff0000, v203
	v_lshlrev_b32_e32 v160, 16, v207
	v_and_b32_e32 v161, 0xffff0000, v207
	v_pk_mul_f32 v[158:159], v[158:159], v[160:161]
	v_pk_mul_f32 v[40:41], v[40:41], v[158:159]
	s_waitcnt vmcnt(0)
	v_lshlrev_b32_e32 v138, 16, v208
	v_and_b32_e32 v139, 0xffff0000, v208
	v_lshlrev_b32_e32 v140, 16, v212
	v_and_b32_e32 v141, 0xffff0000, v212
	v_pk_mul_f32 v[138:139], v[138:139], v[140:141]
	v_pk_mul_f32 v[10:11], v[10:11], v[138:139]
	v_lshlrev_b32_e32 v158, 16, v209
	v_and_b32_e32 v159, 0xffff0000, v209
	v_lshlrev_b32_e32 v160, 16, v213
	v_and_b32_e32 v161, 0xffff0000, v213
	v_pk_mul_f32 v[158:159], v[158:159], v[160:161]
	v_pk_mul_f32 v[12:13], v[12:13], v[158:159]
	v_lshlrev_b32_e32 v138, 16, v210
	v_and_b32_e32 v139, 0xffff0000, v210
	v_lshlrev_b32_e32 v140, 16, v214
	v_and_b32_e32 v141, 0xffff0000, v214
	v_pk_mul_f32 v[138:139], v[138:139], v[140:141]
	v_pk_mul_f32 v[6:7], v[6:7], v[138:139]
	v_lshlrev_b32_e32 v158, 16, v211
	v_and_b32_e32 v159, 0xffff0000, v211
	v_lshlrev_b32_e32 v160, 16, v215
	v_and_b32_e32 v161, 0xffff0000, v215
	v_pk_mul_f32 v[158:159], v[158:159], v[160:161]
	v_pk_mul_f32 v[8:9], v[8:9], v[158:159]
	s_branch .LBB0_778

.LBB0_781:
	s_andn2_b64 vcc, exec, s[0:1]
	s_cbranch_vccnz .LBB0_763
	s_barrier
	s_branch .LBB0_763
.LBB0_784:
	s_waitcnt vmcnt(0)
	v_readlane_b32 s24, v251, 60
	v_readlane_b32 s26, v251, 62
	v_readlane_b32 s28, v250, 0
	v_readlane_b32 s34, v250, 2
	v_readlane_b32 s22, v250, 4
	v_readlane_b32 s30, v250, 6
	v_readlane_b32 s18, v251, 58
	v_readlane_b32 s16, v251, 2
	v_readlane_b32 s25, v251, 61
	v_readlane_b32 s27, v251, 63
	v_readlane_b32 s29, v250, 1
	v_readlane_b32 s35, v250, 3
	v_readlane_b32 s23, v250, 5
	v_readlane_b32 s31, v250, 7
	v_readlane_b32 s19, v251, 59
	v_readlane_b32 s17, v251, 3
	v_readlane_b32 s21, v250, 8
	s_barrier
